# GLA prompt consumer loop hand-scheduled: 32 tokens unrolled, 3-token software pipeline, double-buffered LDS operand prefetch
# speedup vs baseline: 1.0467x; 1.0467x over previous
; #define LAS __attribute__((address_space(3)))
; __device__ __forceinline__ float quad_sum(float v) { v += dppf<0xB1>(v); v += dppf<0x4E>(v); return v; }
; __device__ __forceinline__ void gla_unit(const Params& P, LAS unsigned char* lds, int li, bool sample, int b, int h, const int tid) {
;     ...
;         } else if (j >= 1 && j <= NC) {
;             LAS float* qs = (LAS float*)(lds + ((j - 1) & 1) * SET); LAS float* ks = qs + 1024; LAS float* gs = qs + 2048; LAS float* vs = qs + 3072; LAS float* os = qs + 3072 + 2048;
;             const int ntok = min(MX_CH, L - (j - 1) * MX_CH);
;             f32x4 kk[2], qq[2], gg[2]; float ve;
; #pragma unroll
;             for (int i = 0; i < 2; ++i) { kk[i] = *(const LAS f32x4*)(ks + 8 * dq + 4 * i); qq[i] = *(const LAS f32x4*)(qs + 8 * dq + 4 * i); gg[i] = *(const LAS f32x4*)(gs + 8 * dq + 4 * i); }
;             ve = vs[e];
;             for (int tok = 0; tok < ntok; ++tok) {
;                 const int tn = min(tok + 1, ntok - 1);
;                 f32x4 kn[2], qn[2], gn[2];
; #pragma unroll
;                 for (int i = 0; i < 2; ++i) { kn[i] = *(const LAS f32x4*)(ks + tn * 32 + 8 * dq + 4 * i); qn[i] = *(const LAS f32x4*)(qs + tn * 32 + 8 * dq + 4 * i); gn[i] = *(const LAS f32x4*)(gs + tn * 32 + 8 * dq + 4 * i); }
;                 const float vn = vs[tn * 64 + e];
;                 const f32x2 v2 = (f32x2){ve, ve};
;                 f32x2 oa[2];
; #pragma unroll
;                 for (int i = 0; i < 2; ++i) {
;                     S[2 * i] = S[2 * i] * (f32x2){gg[i][0], gg[i][1]} + (f32x2){kk[i][0], kk[i][1]} * v2; S[2 * i + 1] = S[2 * i + 1] * (f32x2){gg[i][2], gg[i][3]} + (f32x2){kk[i][2], kk[i][3]} * v2;
;                     oa[i] = (f32x2){qq[i][0], qq[i][1]} * S[2 * i] + (f32x2){qq[i][2], qq[i][3]} * S[2 * i + 1];
;                 }
;                 const f32x2 os2 = oa[0] + oa[1];
;                 const float o = quad_sum(os2[0] + os2[1]);
;                 if (dq == 0) os[tok * 64 + e] = o;
; #pragma unroll
;                 for (int i = 0; i < 2; ++i) { kk[i] = kn[i]; qq[i] = qn[i]; gg[i] = gn[i]; }
;                 ve = vn;
;             }
.LBB0_253:
	s_add_i32 s0, s13, -1
	s_cmpk_gt_u32 s0, 0x7f
	v_mov_b32_e32 v31, v71
	v_mov_b32_e32 v30, v70
	v_mov_b32_e32 v33, v69
	v_mov_b32_e32 v32, v68
	v_mov_b32_e32 v35, v67
	v_mov_b32_e32 v34, v66
	v_mov_b32_e32 v37, v65
	v_mov_b32_e32 v36, v40
	s_cbranch_scc1 .LBB0_258
	s_bitcmp1_b32 s0, 0
	s_cselect_b32 s0, 0x7000, 0
	s_add_i32 s1, s0, 0
	v_lshl_add_u32 v120, v60, 2, s1
	v_lshl_add_u32 v121, v58, 2, s1
	s_waitcnt vmcnt(0)
	s_mov_b64 s[0:1], exec
	ds_read_b128 v[80:83], v120 offset:4096
	ds_read_b128 v[84:87], v120 offset:4112
	ds_read_b32 v112, v121 offset:12288
	ds_read_b128 v[16:19], v120 offset:8192
	ds_read_b128 v[20:23], v120 offset:8208
	ds_read_b128 v[88:91], v120 offset:4224
	ds_read_b128 v[92:95], v120 offset:4240
	ds_read_b32 v114, v121 offset:12544
	ds_read_b128 v[72:75], v120 offset:8320
	ds_read_b128 v[76:79], v120 offset:8336
	ds_read_b128 v[0:3], v120 offset:0
	ds_read_b128 v[4:7], v120 offset:16
	ds_read_b128 v[8:11], v120 offset:128
	ds_read_b128 v[12:15], v120 offset:144
	s_waitcnt lgkmcnt(11)
	v_pk_mul_f32 v[96:97], v[112:113], v[80:81] op_sel_hi:[0,1]
	v_pk_mul_f32 v[98:99], v[112:113], v[82:83] op_sel_hi:[0,1]
	v_pk_mul_f32 v[100:101], v[112:113], v[84:85] op_sel_hi:[0,1]
	v_pk_mul_f32 v[102:103], v[112:113], v[86:87] op_sel_hi:[0,1]
	ds_read_b128 v[80:83], v120 offset:4352
	ds_read_b128 v[84:87], v120 offset:4368
	ds_read_b32 v112, v121 offset:12800
	s_waitcnt lgkmcnt(9)
	v_pk_fma_f32 v[36:37], v[16:17], v[36:37], v[96:97]
	v_pk_fma_f32 v[34:35], v[18:19], v[34:35], v[98:99]
	v_pk_fma_f32 v[32:33], v[20:21], v[32:33], v[100:101]
	v_pk_fma_f32 v[30:31], v[22:23], v[30:31], v[102:103]
	ds_read_b128 v[16:19], v120 offset:8448
	ds_read_b128 v[20:23], v120 offset:8464
	v_pk_mul_f32 v[104:105], v[114:115], v[88:89] op_sel_hi:[0,1]
	v_pk_mul_f32 v[106:107], v[114:115], v[90:91] op_sel_hi:[0,1]
	v_pk_mul_f32 v[108:109], v[114:115], v[92:93] op_sel_hi:[0,1]
	v_pk_mul_f32 v[110:111], v[114:115], v[94:95] op_sel_hi:[0,1]
	ds_read_b128 v[88:91], v120 offset:4480
	ds_read_b128 v[92:95], v120 offset:4496
	ds_read_b32 v114, v121 offset:13056
	s_waitcnt lgkmcnt(5)
	v_pk_mul_f32 v[116:117], v[0:1], v[36:37]
	v_pk_fma_f32 v[36:37], v[72:73], v[36:37], v[104:105]
	v_pk_mul_f32 v[118:119], v[2:3], v[34:35]
	v_pk_fma_f32 v[34:35], v[74:75], v[34:35], v[106:107]
	v_pk_fma_f32 v[116:117], v[4:5], v[32:33], v[116:117]
	v_pk_fma_f32 v[32:33], v[76:77], v[32:33], v[108:109]
	v_pk_fma_f32 v[118:119], v[6:7], v[30:31], v[118:119]
	v_pk_fma_f32 v[30:31], v[78:79], v[30:31], v[110:111]
	ds_read_b128 v[0:3], v120 offset:256
	ds_read_b128 v[4:7], v120 offset:272
	ds_read_b128 v[72:75], v120 offset:8576
	ds_read_b128 v[76:79], v120 offset:8592
	v_pk_add_f32 v[116:117], v[116:117], v[118:119]
	v_pk_mul_f32 v[96:97], v[112:113], v[80:81] op_sel_hi:[0,1]
	v_pk_mul_f32 v[98:99], v[112:113], v[82:83] op_sel_hi:[0,1]
	v_add_f32_e32 v116, v116, v117
	v_pk_mul_f32 v[100:101], v[112:113], v[84:85] op_sel_hi:[0,1]
	v_pk_mul_f32 v[102:103], v[112:113], v[86:87] op_sel_hi:[0,1]
	v_add_f32_dpp v116, v116, v116 quad_perm:[1,0,3,2] row_mask:0xf bank_mask:0xf bound_ctrl:1
	ds_read_b128 v[80:83], v120 offset:4608
	ds_read_b128 v[84:87], v120 offset:4624
	ds_read_b32 v112, v121 offset:13312
	v_add_f32_dpp v116, v116, v116 quad_perm:[2,3,0,1] row_mask:0xf bank_mask:0xf bound_ctrl:1
	s_mov_b64 exec, s[38:39]
	ds_write_b32 v121, v116 offset:20480
	s_mov_b64 exec, s[0:1]
	s_waitcnt lgkmcnt(8)
	v_pk_mul_f32 v[116:117], v[8:9], v[36:37]
	v_pk_fma_f32 v[36:37], v[16:17], v[36:37], v[96:97]
	v_pk_mul_f32 v[118:119], v[10:11], v[34:35]
	v_pk_fma_f32 v[34:35], v[18:19], v[34:35], v[98:99]
	v_pk_fma_f32 v[116:117], v[12:13], v[32:33], v[116:117]
	v_pk_fma_f32 v[32:33], v[20:21], v[32:33], v[100:101]
	v_pk_fma_f32 v[118:119], v[14:15], v[30:31], v[118:119]
	v_pk_fma_f32 v[30:31], v[22:23], v[30:31], v[102:103]
	ds_read_b128 v[8:11], v120 offset:384
	ds_read_b128 v[12:15], v120 offset:400
	ds_read_b128 v[16:19], v120 offset:8704
	ds_read_b128 v[20:23], v120 offset:8720
	v_pk_add_f32 v[116:117], v[116:117], v[118:119]
	v_pk_mul_f32 v[104:105], v[114:115], v[88:89] op_sel_hi:[0,1]
	v_pk_mul_f32 v[106:107], v[114:115], v[90:91] op_sel_hi:[0,1]
	v_add_f32_e32 v116, v116, v117
	v_pk_mul_f32 v[108:109], v[114:115], v[92:93] op_sel_hi:[0,1]
	v_pk_mul_f32 v[110:111], v[114:115], v[94:95] op_sel_hi:[0,1]
	v_add_f32_dpp v116, v116, v116 quad_perm:[1,0,3,2] row_mask:0xf bank_mask:0xf bound_ctrl:1
	ds_read_b128 v[88:91], v120 offset:4736
	ds_read_b128 v[92:95], v120 offset:4752
	ds_read_b32 v114, v121 offset:13568
	v_add_f32_dpp v116, v116, v116 quad_perm:[2,3,0,1] row_mask:0xf bank_mask:0xf bound_ctrl:1
	s_mov_b64 exec, s[38:39]
	s_waitcnt lgkmcnt(11)
	ds_write_b32 v121, v116 offset:20736
	s_mov_b64 exec, s[0:1]
	s_waitcnt lgkmcnt(9)
	v_pk_mul_f32 v[116:117], v[0:1], v[36:37]
	v_pk_fma_f32 v[36:37], v[72:73], v[36:37], v[104:105]
	v_pk_mul_f32 v[118:119], v[2:3], v[34:35]
	v_pk_fma_f32 v[34:35], v[74:75], v[34:35], v[106:107]
	v_pk_fma_f32 v[116:117], v[4:5], v[32:33], v[116:117]
	v_pk_fma_f32 v[32:33], v[76:77], v[32:33], v[108:109]
	v_pk_fma_f32 v[118:119], v[6:7], v[30:31], v[118:119]
	v_pk_fma_f32 v[30:31], v[78:79], v[30:31], v[110:111]
	ds_read_b128 v[0:3], v120 offset:512
	ds_read_b128 v[4:7], v120 offset:528
	ds_read_b128 v[72:75], v120 offset:8832
	ds_read_b128 v[76:79], v120 offset:8848
	v_pk_add_f32 v[116:117], v[116:117], v[118:119]
	v_pk_mul_f32 v[96:97], v[112:113], v[80:81] op_sel_hi:[0,1]
	v_pk_mul_f32 v[98:99], v[112:113], v[82:83] op_sel_hi:[0,1]
	v_add_f32_e32 v116, v116, v117
	v_pk_mul_f32 v[100:101], v[112:113], v[84:85] op_sel_hi:[0,1]
	v_pk_mul_f32 v[102:103], v[112:113], v[86:87] op_sel_hi:[0,1]
	v_add_f32_dpp v116, v116, v116 quad_perm:[1,0,3,2] row_mask:0xf bank_mask:0xf bound_ctrl:1
	ds_read_b128 v[80:83], v120 offset:4864
	ds_read_b128 v[84:87], v120 offset:4880
	s_waitcnt lgkmcnt(11)
; #define LAS __attribute__((address_space(3)))
; __device__ __forceinline__ float quad_sum(float v) { v += dppf<0xB1>(v); v += dppf<0x4E>(v); return v; }
; __device__ __forceinline__ void gla_unit(const Params& P, LAS unsigned char* lds, int li, bool sample, int b, int h, const int tid) {
;     ...
;             for (int tok = 0; tok < ntok; ++tok) {
;                 const int tn = min(tok + 1, ntok - 1);
;                 f32x4 kn[2], qn[2], gn[2];
; #pragma unroll
;                 for (int i = 0; i < 2; ++i) { kn[i] = *(const LAS f32x4*)(ks + tn * 32 + 8 * dq + 4 * i); qn[i] = *(const LAS f32x4*)(qs + tn * 32 + 8 * dq + 4 * i); gn[i] = *(const LAS f32x4*)(gs + tn * 32 + 8 * dq + 4 * i); }
;                 const float vn = vs[tn * 64 + e];
;                 const f32x2 v2 = (f32x2){ve, ve};
;                 f32x2 oa[2];
; #pragma unroll
;                 for (int i = 0; i < 2; ++i) {
;                     S[2 * i] = S[2 * i] * (f32x2){gg[i][0], gg[i][1]} + (f32x2){kk[i][0], kk[i][1]} * v2; S[2 * i + 1] = S[2 * i + 1] * (f32x2){gg[i][2], gg[i][3]} + (f32x2){kk[i][2], kk[i][3]} * v2;
;                     oa[i] = (f32x2){qq[i][0], qq[i][1]} * S[2 * i] + (f32x2){qq[i][2], qq[i][3]} * S[2 * i + 1];
;                 }
;                 const f32x2 os2 = oa[0] + oa[1];
;                 const float o = quad_sum(os2[0] + os2[1]);
;                 if (dq == 0) os[tok * 64 + e] = o;
; #pragma unroll
;                 for (int i = 0; i < 2; ++i) { kk[i] = kn[i]; qq[i] = qn[i]; gg[i] = gn[i]; }
;                 ve = vn;
	ds_read_b32 v112, v121 offset:13824
	v_add_f32_dpp v116, v116, v116 quad_perm:[2,3,0,1] row_mask:0xf bank_mask:0xf bound_ctrl:1
	s_mov_b64 exec, s[38:39]
	ds_write_b32 v121, v116 offset:20992
	s_mov_b64 exec, s[0:1]
	s_waitcnt lgkmcnt(9)
	v_pk_mul_f32 v[116:117], v[8:9], v[36:37]
	v_pk_fma_f32 v[36:37], v[16:17], v[36:37], v[96:97]
	v_pk_mul_f32 v[118:119], v[10:11], v[34:35]
	v_pk_fma_f32 v[34:35], v[18:19], v[34:35], v[98:99]
	v_pk_fma_f32 v[116:117], v[12:13], v[32:33], v[116:117]
	v_pk_fma_f32 v[32:33], v[20:21], v[32:33], v[100:101]
	v_pk_fma_f32 v[118:119], v[14:15], v[30:31], v[118:119]
	v_pk_fma_f32 v[30:31], v[22:23], v[30:31], v[102:103]
	ds_read_b128 v[8:11], v120 offset:640
	ds_read_b128 v[12:15], v120 offset:656
	ds_read_b128 v[16:19], v120 offset:8960
	ds_read_b128 v[20:23], v120 offset:8976
	v_pk_add_f32 v[116:117], v[116:117], v[118:119]
	v_pk_mul_f32 v[104:105], v[114:115], v[88:89] op_sel_hi:[0,1]
	v_pk_mul_f32 v[106:107], v[114:115], v[90:91] op_sel_hi:[0,1]
	v_add_f32_e32 v116, v116, v117
	v_pk_mul_f32 v[108:109], v[114:115], v[92:93] op_sel_hi:[0,1]
	v_pk_mul_f32 v[110:111], v[114:115], v[94:95] op_sel_hi:[0,1]
	v_add_f32_dpp v116, v116, v116 quad_perm:[1,0,3,2] row_mask:0xf bank_mask:0xf bound_ctrl:1
	ds_read_b128 v[88:91], v120 offset:4992
	ds_read_b128 v[92:95], v120 offset:5008
	s_waitcnt lgkmcnt(11)
	ds_read_b32 v114, v121 offset:14080
	v_add_f32_dpp v116, v116, v116 quad_perm:[2,3,0,1] row_mask:0xf bank_mask:0xf bound_ctrl:1
	s_mov_b64 exec, s[38:39]
	ds_write_b32 v121, v116 offset:21248
	s_mov_b64 exec, s[0:1]
	s_waitcnt lgkmcnt(9)
	v_pk_mul_f32 v[116:117], v[0:1], v[36:37]
	v_pk_fma_f32 v[36:37], v[72:73], v[36:37], v[104:105]
	v_pk_mul_f32 v[118:119], v[2:3], v[34:35]
	v_pk_fma_f32 v[34:35], v[74:75], v[34:35], v[106:107]
	v_pk_fma_f32 v[116:117], v[4:5], v[32:33], v[116:117]
	v_pk_fma_f32 v[32:33], v[76:77], v[32:33], v[108:109]
	v_pk_fma_f32 v[118:119], v[6:7], v[30:31], v[118:119]
	v_pk_fma_f32 v[30:31], v[78:79], v[30:31], v[110:111]
	ds_read_b128 v[0:3], v120 offset:768
	ds_read_b128 v[4:7], v120 offset:784
	ds_read_b128 v[72:75], v120 offset:9088
	ds_read_b128 v[76:79], v120 offset:9104
	v_pk_add_f32 v[116:117], v[116:117], v[118:119]
	v_pk_mul_f32 v[96:97], v[112:113], v[80:81] op_sel_hi:[0,1]
	v_pk_mul_f32 v[98:99], v[112:113], v[82:83] op_sel_hi:[0,1]
	v_add_f32_e32 v116, v116, v117
	v_pk_mul_f32 v[100:101], v[112:113], v[84:85] op_sel_hi:[0,1]
	v_pk_mul_f32 v[102:103], v[112:113], v[86:87] op_sel_hi:[0,1]
	v_add_f32_dpp v116, v116, v116 quad_perm:[1,0,3,2] row_mask:0xf bank_mask:0xf bound_ctrl:1
	ds_read_b128 v[80:83], v120 offset:5120
	ds_read_b128 v[84:87], v120 offset:5136
	s_waitcnt lgkmcnt(11)
	ds_read_b32 v112, v121 offset:14336
	v_add_f32_dpp v116, v116, v116 quad_perm:[2,3,0,1] row_mask:0xf bank_mask:0xf bound_ctrl:1
	s_mov_b64 exec, s[38:39]
	ds_write_b32 v121, v116 offset:21504
	s_mov_b64 exec, s[0:1]
	s_waitcnt lgkmcnt(9)
	v_pk_mul_f32 v[116:117], v[8:9], v[36:37]
	v_pk_fma_f32 v[36:37], v[16:17], v[36:37], v[96:97]
	v_pk_mul_f32 v[118:119], v[10:11], v[34:35]
	v_pk_fma_f32 v[34:35], v[18:19], v[34:35], v[98:99]
	v_pk_fma_f32 v[116:117], v[12:13], v[32:33], v[116:117]
	v_pk_fma_f32 v[32:33], v[20:21], v[32:33], v[100:101]
	v_pk_fma_f32 v[118:119], v[14:15], v[30:31], v[118:119]
	v_pk_fma_f32 v[30:31], v[22:23], v[30:31], v[102:103]
	ds_read_b128 v[8:11], v120 offset:896
	ds_read_b128 v[12:15], v120 offset:912
	ds_read_b128 v[16:19], v120 offset:9216
	ds_read_b128 v[20:23], v120 offset:9232
	v_pk_add_f32 v[116:117], v[116:117], v[118:119]
	v_pk_mul_f32 v[104:105], v[114:115], v[88:89] op_sel_hi:[0,1]
	v_pk_mul_f32 v[106:107], v[114:115], v[90:91] op_sel_hi:[0,1]
	v_add_f32_e32 v116, v116, v117
	v_pk_mul_f32 v[108:109], v[114:115], v[92:93] op_sel_hi:[0,1]
	v_pk_mul_f32 v[110:111], v[114:115], v[94:95] op_sel_hi:[0,1]
	v_add_f32_dpp v116, v116, v116 quad_perm:[1,0,3,2] row_mask:0xf bank_mask:0xf bound_ctrl:1
	ds_read_b128 v[88:91], v120 offset:5248
	ds_read_b128 v[92:95], v120 offset:5264
	s_waitcnt lgkmcnt(11)
	ds_read_b32 v114, v121 offset:14592
	v_add_f32_dpp v116, v116, v116 quad_perm:[2,3,0,1] row_mask:0xf bank_mask:0xf bound_ctrl:1
	s_mov_b64 exec, s[38:39]
	ds_write_b32 v121, v116 offset:21760
	s_mov_b64 exec, s[0:1]
	s_waitcnt lgkmcnt(9)
	v_pk_mul_f32 v[116:117], v[0:1], v[36:37]
	v_pk_fma_f32 v[36:37], v[72:73], v[36:37], v[104:105]
	v_pk_mul_f32 v[118:119], v[2:3], v[34:35]
	v_pk_fma_f32 v[34:35], v[74:75], v[34:35], v[106:107]
	v_pk_fma_f32 v[116:117], v[4:5], v[32:33], v[116:117]
	v_pk_fma_f32 v[32:33], v[76:77], v[32:33], v[108:109]
	v_pk_fma_f32 v[118:119], v[6:7], v[30:31], v[118:119]
	v_pk_fma_f32 v[30:31], v[78:79], v[30:31], v[110:111]
	ds_read_b128 v[0:3], v120 offset:1024
	ds_read_b128 v[4:7], v120 offset:1040
	ds_read_b128 v[72:75], v120 offset:9344
	ds_read_b128 v[76:79], v120 offset:9360
	v_pk_add_f32 v[116:117], v[116:117], v[118:119]
	v_pk_mul_f32 v[96:97], v[112:113], v[80:81] op_sel_hi:[0,1]
	v_pk_mul_f32 v[98:99], v[112:113], v[82:83] op_sel_hi:[0,1]
	v_add_f32_e32 v116, v116, v117
	v_pk_mul_f32 v[100:101], v[112:113], v[84:85] op_sel_hi:[0,1]
	v_pk_mul_f32 v[102:103], v[112:113], v[86:87] op_sel_hi:[0,1]
	v_add_f32_dpp v116, v116, v116 quad_perm:[1,0,3,2] row_mask:0xf bank_mask:0xf bound_ctrl:1
	ds_read_b128 v[80:83], v120 offset:5376
	ds_read_b128 v[84:87], v120 offset:5392
	s_waitcnt lgkmcnt(11)
	ds_read_b32 v112, v121 offset:14848
	v_add_f32_dpp v116, v116, v116 quad_perm:[2,3,0,1] row_mask:0xf bank_mask:0xf bound_ctrl:1
	s_mov_b64 exec, s[38:39]
	ds_write_b32 v121, v116 offset:22016
	s_mov_b64 exec, s[0:1]
	s_waitcnt lgkmcnt(9)
; #define LAS __attribute__((address_space(3)))
; __device__ __forceinline__ float quad_sum(float v) { v += dppf<0xB1>(v); v += dppf<0x4E>(v); return v; }
; __device__ __forceinline__ void gla_unit(const Params& P, LAS unsigned char* lds, int li, bool sample, int b, int h, const int tid) {
;     ...
;             for (int tok = 0; tok < ntok; ++tok) {
;                 const int tn = min(tok + 1, ntok - 1);
;                 f32x4 kn[2], qn[2], gn[2];
; #pragma unroll
;                 for (int i = 0; i < 2; ++i) { kn[i] = *(const LAS f32x4*)(ks + tn * 32 + 8 * dq + 4 * i); qn[i] = *(const LAS f32x4*)(qs + tn * 32 + 8 * dq + 4 * i); gn[i] = *(const LAS f32x4*)(gs + tn * 32 + 8 * dq + 4 * i); }
;                 const float vn = vs[tn * 64 + e];
;                 const f32x2 v2 = (f32x2){ve, ve};
;                 f32x2 oa[2];
; #pragma unroll
;                 for (int i = 0; i < 2; ++i) {
;                     S[2 * i] = S[2 * i] * (f32x2){gg[i][0], gg[i][1]} + (f32x2){kk[i][0], kk[i][1]} * v2; S[2 * i + 1] = S[2 * i + 1] * (f32x2){gg[i][2], gg[i][3]} + (f32x2){kk[i][2], kk[i][3]} * v2;
;                     oa[i] = (f32x2){qq[i][0], qq[i][1]} * S[2 * i] + (f32x2){qq[i][2], qq[i][3]} * S[2 * i + 1];
;                 }
;                 const f32x2 os2 = oa[0] + oa[1];
;                 const float o = quad_sum(os2[0] + os2[1]);
;                 if (dq == 0) os[tok * 64 + e] = o;
; #pragma unroll
;                 for (int i = 0; i < 2; ++i) { kk[i] = kn[i]; qq[i] = qn[i]; gg[i] = gn[i]; }
;                 ve = vn;
	v_pk_mul_f32 v[116:117], v[8:9], v[36:37]
	v_pk_fma_f32 v[36:37], v[16:17], v[36:37], v[96:97]
	v_pk_mul_f32 v[118:119], v[10:11], v[34:35]
	v_pk_fma_f32 v[34:35], v[18:19], v[34:35], v[98:99]
	v_pk_fma_f32 v[116:117], v[12:13], v[32:33], v[116:117]
	v_pk_fma_f32 v[32:33], v[20:21], v[32:33], v[100:101]
	v_pk_fma_f32 v[118:119], v[14:15], v[30:31], v[118:119]
	v_pk_fma_f32 v[30:31], v[22:23], v[30:31], v[102:103]
	ds_read_b128 v[8:11], v120 offset:1152
	ds_read_b128 v[12:15], v120 offset:1168
	ds_read_b128 v[16:19], v120 offset:9472
	ds_read_b128 v[20:23], v120 offset:9488
	v_pk_add_f32 v[116:117], v[116:117], v[118:119]
	v_pk_mul_f32 v[104:105], v[114:115], v[88:89] op_sel_hi:[0,1]
	v_pk_mul_f32 v[106:107], v[114:115], v[90:91] op_sel_hi:[0,1]
	v_add_f32_e32 v116, v116, v117
	v_pk_mul_f32 v[108:109], v[114:115], v[92:93] op_sel_hi:[0,1]
	v_pk_mul_f32 v[110:111], v[114:115], v[94:95] op_sel_hi:[0,1]
	v_add_f32_dpp v116, v116, v116 quad_perm:[1,0,3,2] row_mask:0xf bank_mask:0xf bound_ctrl:1
	ds_read_b128 v[88:91], v120 offset:5504
	ds_read_b128 v[92:95], v120 offset:5520
	s_waitcnt lgkmcnt(11)
	ds_read_b32 v114, v121 offset:15104
	v_add_f32_dpp v116, v116, v116 quad_perm:[2,3,0,1] row_mask:0xf bank_mask:0xf bound_ctrl:1
	s_mov_b64 exec, s[38:39]
	ds_write_b32 v121, v116 offset:22272
	s_mov_b64 exec, s[0:1]
	s_waitcnt lgkmcnt(9)
	v_pk_mul_f32 v[116:117], v[0:1], v[36:37]
	v_pk_fma_f32 v[36:37], v[72:73], v[36:37], v[104:105]
	v_pk_mul_f32 v[118:119], v[2:3], v[34:35]
	v_pk_fma_f32 v[34:35], v[74:75], v[34:35], v[106:107]
	v_pk_fma_f32 v[116:117], v[4:5], v[32:33], v[116:117]
	v_pk_fma_f32 v[32:33], v[76:77], v[32:33], v[108:109]
	v_pk_fma_f32 v[118:119], v[6:7], v[30:31], v[118:119]
	v_pk_fma_f32 v[30:31], v[78:79], v[30:31], v[110:111]
	ds_read_b128 v[0:3], v120 offset:1280
	ds_read_b128 v[4:7], v120 offset:1296
	ds_read_b128 v[72:75], v120 offset:9600
	ds_read_b128 v[76:79], v120 offset:9616
	v_pk_add_f32 v[116:117], v[116:117], v[118:119]
	v_pk_mul_f32 v[96:97], v[112:113], v[80:81] op_sel_hi:[0,1]
	v_pk_mul_f32 v[98:99], v[112:113], v[82:83] op_sel_hi:[0,1]
	v_add_f32_e32 v116, v116, v117
	v_pk_mul_f32 v[100:101], v[112:113], v[84:85] op_sel_hi:[0,1]
	v_pk_mul_f32 v[102:103], v[112:113], v[86:87] op_sel_hi:[0,1]
	v_add_f32_dpp v116, v116, v116 quad_perm:[1,0,3,2] row_mask:0xf bank_mask:0xf bound_ctrl:1
	ds_read_b128 v[80:83], v120 offset:5632
	ds_read_b128 v[84:87], v120 offset:5648
	s_waitcnt lgkmcnt(11)
	ds_read_b32 v112, v121 offset:15360
	v_add_f32_dpp v116, v116, v116 quad_perm:[2,3,0,1] row_mask:0xf bank_mask:0xf bound_ctrl:1
	s_mov_b64 exec, s[38:39]
	ds_write_b32 v121, v116 offset:22528
	s_mov_b64 exec, s[0:1]
	s_waitcnt lgkmcnt(9)
	v_pk_mul_f32 v[116:117], v[8:9], v[36:37]
	v_pk_fma_f32 v[36:37], v[16:17], v[36:37], v[96:97]
	v_pk_mul_f32 v[118:119], v[10:11], v[34:35]
	v_pk_fma_f32 v[34:35], v[18:19], v[34:35], v[98:99]
	v_pk_fma_f32 v[116:117], v[12:13], v[32:33], v[116:117]
	v_pk_fma_f32 v[32:33], v[20:21], v[32:33], v[100:101]
	v_pk_fma_f32 v[118:119], v[14:15], v[30:31], v[118:119]
	v_pk_fma_f32 v[30:31], v[22:23], v[30:31], v[102:103]
	ds_read_b128 v[8:11], v120 offset:1408
	ds_read_b128 v[12:15], v120 offset:1424
	ds_read_b128 v[16:19], v120 offset:9728
	ds_read_b128 v[20:23], v120 offset:9744
	v_pk_add_f32 v[116:117], v[116:117], v[118:119]
	v_pk_mul_f32 v[104:105], v[114:115], v[88:89] op_sel_hi:[0,1]
	v_pk_mul_f32 v[106:107], v[114:115], v[90:91] op_sel_hi:[0,1]
	v_add_f32_e32 v116, v116, v117
	v_pk_mul_f32 v[108:109], v[114:115], v[92:93] op_sel_hi:[0,1]
	v_pk_mul_f32 v[110:111], v[114:115], v[94:95] op_sel_hi:[0,1]
	v_add_f32_dpp v116, v116, v116 quad_perm:[1,0,3,2] row_mask:0xf bank_mask:0xf bound_ctrl:1
	ds_read_b128 v[88:91], v120 offset:5760
	ds_read_b128 v[92:95], v120 offset:5776
	s_waitcnt lgkmcnt(11)
	ds_read_b32 v114, v121 offset:15616
	v_add_f32_dpp v116, v116, v116 quad_perm:[2,3,0,1] row_mask:0xf bank_mask:0xf bound_ctrl:1
	s_mov_b64 exec, s[38:39]
	ds_write_b32 v121, v116 offset:22784
	s_mov_b64 exec, s[0:1]
	s_waitcnt lgkmcnt(9)
	v_pk_mul_f32 v[116:117], v[0:1], v[36:37]
	v_pk_fma_f32 v[36:37], v[72:73], v[36:37], v[104:105]
	v_pk_mul_f32 v[118:119], v[2:3], v[34:35]
	v_pk_fma_f32 v[34:35], v[74:75], v[34:35], v[106:107]
	v_pk_fma_f32 v[116:117], v[4:5], v[32:33], v[116:117]
	v_pk_fma_f32 v[32:33], v[76:77], v[32:33], v[108:109]
	v_pk_fma_f32 v[118:119], v[6:7], v[30:31], v[118:119]
	v_pk_fma_f32 v[30:31], v[78:79], v[30:31], v[110:111]
	ds_read_b128 v[0:3], v120 offset:1536
	ds_read_b128 v[4:7], v120 offset:1552
	ds_read_b128 v[72:75], v120 offset:9856
	ds_read_b128 v[76:79], v120 offset:9872
	v_pk_add_f32 v[116:117], v[116:117], v[118:119]
	v_pk_mul_f32 v[96:97], v[112:113], v[80:81] op_sel_hi:[0,1]
	v_pk_mul_f32 v[98:99], v[112:113], v[82:83] op_sel_hi:[0,1]
	v_add_f32_e32 v116, v116, v117
	v_pk_mul_f32 v[100:101], v[112:113], v[84:85] op_sel_hi:[0,1]
	v_pk_mul_f32 v[102:103], v[112:113], v[86:87] op_sel_hi:[0,1]
	v_add_f32_dpp v116, v116, v116 quad_perm:[1,0,3,2] row_mask:0xf bank_mask:0xf bound_ctrl:1
	ds_read_b128 v[80:83], v120 offset:5888
	ds_read_b128 v[84:87], v120 offset:5904
	s_waitcnt lgkmcnt(11)
	ds_read_b32 v112, v121 offset:15872
	v_add_f32_dpp v116, v116, v116 quad_perm:[2,3,0,1] row_mask:0xf bank_mask:0xf bound_ctrl:1
	s_mov_b64 exec, s[38:39]
	ds_write_b32 v121, v116 offset:23040
	s_mov_b64 exec, s[0:1]
	s_waitcnt lgkmcnt(9)
; #define LAS __attribute__((address_space(3)))
; __device__ __forceinline__ float quad_sum(float v) { v += dppf<0xB1>(v); v += dppf<0x4E>(v); return v; }
; __device__ __forceinline__ void gla_unit(const Params& P, LAS unsigned char* lds, int li, bool sample, int b, int h, const int tid) {
;     ...
;             for (int tok = 0; tok < ntok; ++tok) {
;                 const int tn = min(tok + 1, ntok - 1);
;                 f32x4 kn[2], qn[2], gn[2];
; #pragma unroll
;                 for (int i = 0; i < 2; ++i) { kn[i] = *(const LAS f32x4*)(ks + tn * 32 + 8 * dq + 4 * i); qn[i] = *(const LAS f32x4*)(qs + tn * 32 + 8 * dq + 4 * i); gn[i] = *(const LAS f32x4*)(gs + tn * 32 + 8 * dq + 4 * i); }
;                 const float vn = vs[tn * 64 + e];
;                 const f32x2 v2 = (f32x2){ve, ve};
;                 f32x2 oa[2];
; #pragma unroll
;                 for (int i = 0; i < 2; ++i) {
;                     S[2 * i] = S[2 * i] * (f32x2){gg[i][0], gg[i][1]} + (f32x2){kk[i][0], kk[i][1]} * v2; S[2 * i + 1] = S[2 * i + 1] * (f32x2){gg[i][2], gg[i][3]} + (f32x2){kk[i][2], kk[i][3]} * v2;
;                     oa[i] = (f32x2){qq[i][0], qq[i][1]} * S[2 * i] + (f32x2){qq[i][2], qq[i][3]} * S[2 * i + 1];
;                 }
;                 const f32x2 os2 = oa[0] + oa[1];
;                 const float o = quad_sum(os2[0] + os2[1]);
;                 if (dq == 0) os[tok * 64 + e] = o;
; #pragma unroll
;                 for (int i = 0; i < 2; ++i) { kk[i] = kn[i]; qq[i] = qn[i]; gg[i] = gn[i]; }
;                 ve = vn;
	v_pk_mul_f32 v[116:117], v[8:9], v[36:37]
	v_pk_fma_f32 v[36:37], v[16:17], v[36:37], v[96:97]
	v_pk_mul_f32 v[118:119], v[10:11], v[34:35]
	v_pk_fma_f32 v[34:35], v[18:19], v[34:35], v[98:99]
	v_pk_fma_f32 v[116:117], v[12:13], v[32:33], v[116:117]
	v_pk_fma_f32 v[32:33], v[20:21], v[32:33], v[100:101]
	v_pk_fma_f32 v[118:119], v[14:15], v[30:31], v[118:119]
	v_pk_fma_f32 v[30:31], v[22:23], v[30:31], v[102:103]
	ds_read_b128 v[8:11], v120 offset:1664
	ds_read_b128 v[12:15], v120 offset:1680
	ds_read_b128 v[16:19], v120 offset:9984
	ds_read_b128 v[20:23], v120 offset:10000
	v_pk_add_f32 v[116:117], v[116:117], v[118:119]
	v_pk_mul_f32 v[104:105], v[114:115], v[88:89] op_sel_hi:[0,1]
	v_pk_mul_f32 v[106:107], v[114:115], v[90:91] op_sel_hi:[0,1]
	v_add_f32_e32 v116, v116, v117
	v_pk_mul_f32 v[108:109], v[114:115], v[92:93] op_sel_hi:[0,1]
	v_pk_mul_f32 v[110:111], v[114:115], v[94:95] op_sel_hi:[0,1]
	v_add_f32_dpp v116, v116, v116 quad_perm:[1,0,3,2] row_mask:0xf bank_mask:0xf bound_ctrl:1
	ds_read_b128 v[88:91], v120 offset:6016
	ds_read_b128 v[92:95], v120 offset:6032
	s_waitcnt lgkmcnt(11)
	ds_read_b32 v114, v121 offset:16128
	v_add_f32_dpp v116, v116, v116 quad_perm:[2,3,0,1] row_mask:0xf bank_mask:0xf bound_ctrl:1
	s_mov_b64 exec, s[38:39]
	ds_write_b32 v121, v116 offset:23296
	s_mov_b64 exec, s[0:1]
	s_waitcnt lgkmcnt(9)
	v_pk_mul_f32 v[116:117], v[0:1], v[36:37]
	v_pk_fma_f32 v[36:37], v[72:73], v[36:37], v[104:105]
	v_pk_mul_f32 v[118:119], v[2:3], v[34:35]
	v_pk_fma_f32 v[34:35], v[74:75], v[34:35], v[106:107]
	v_pk_fma_f32 v[116:117], v[4:5], v[32:33], v[116:117]
	v_pk_fma_f32 v[32:33], v[76:77], v[32:33], v[108:109]
	v_pk_fma_f32 v[118:119], v[6:7], v[30:31], v[118:119]
	v_pk_fma_f32 v[30:31], v[78:79], v[30:31], v[110:111]
	ds_read_b128 v[0:3], v120 offset:1792
	ds_read_b128 v[4:7], v120 offset:1808
	ds_read_b128 v[72:75], v120 offset:10112
	ds_read_b128 v[76:79], v120 offset:10128
	v_pk_add_f32 v[116:117], v[116:117], v[118:119]
	v_pk_mul_f32 v[96:97], v[112:113], v[80:81] op_sel_hi:[0,1]
	v_pk_mul_f32 v[98:99], v[112:113], v[82:83] op_sel_hi:[0,1]
	v_add_f32_e32 v116, v116, v117
	v_pk_mul_f32 v[100:101], v[112:113], v[84:85] op_sel_hi:[0,1]
	v_pk_mul_f32 v[102:103], v[112:113], v[86:87] op_sel_hi:[0,1]
	v_add_f32_dpp v116, v116, v116 quad_perm:[1,0,3,2] row_mask:0xf bank_mask:0xf bound_ctrl:1
	ds_read_b128 v[80:83], v120 offset:6144
	ds_read_b128 v[84:87], v120 offset:6160
	s_waitcnt lgkmcnt(11)
	ds_read_b32 v112, v121 offset:16384
	v_add_f32_dpp v116, v116, v116 quad_perm:[2,3,0,1] row_mask:0xf bank_mask:0xf bound_ctrl:1
	s_mov_b64 exec, s[38:39]
	ds_write_b32 v121, v116 offset:23552
	s_mov_b64 exec, s[0:1]
	s_waitcnt lgkmcnt(9)
	v_pk_mul_f32 v[116:117], v[8:9], v[36:37]
	v_pk_fma_f32 v[36:37], v[16:17], v[36:37], v[96:97]
	v_pk_mul_f32 v[118:119], v[10:11], v[34:35]
	v_pk_fma_f32 v[34:35], v[18:19], v[34:35], v[98:99]
	v_pk_fma_f32 v[116:117], v[12:13], v[32:33], v[116:117]
	v_pk_fma_f32 v[32:33], v[20:21], v[32:33], v[100:101]
	v_pk_fma_f32 v[118:119], v[14:15], v[30:31], v[118:119]
	v_pk_fma_f32 v[30:31], v[22:23], v[30:31], v[102:103]
	ds_read_b128 v[8:11], v120 offset:1920
	ds_read_b128 v[12:15], v120 offset:1936
	ds_read_b128 v[16:19], v120 offset:10240
	ds_read_b128 v[20:23], v120 offset:10256
	v_pk_add_f32 v[116:117], v[116:117], v[118:119]
	v_pk_mul_f32 v[104:105], v[114:115], v[88:89] op_sel_hi:[0,1]
	v_pk_mul_f32 v[106:107], v[114:115], v[90:91] op_sel_hi:[0,1]
	v_add_f32_e32 v116, v116, v117
	v_pk_mul_f32 v[108:109], v[114:115], v[92:93] op_sel_hi:[0,1]
	v_pk_mul_f32 v[110:111], v[114:115], v[94:95] op_sel_hi:[0,1]
	v_add_f32_dpp v116, v116, v116 quad_perm:[1,0,3,2] row_mask:0xf bank_mask:0xf bound_ctrl:1
	ds_read_b128 v[88:91], v120 offset:6272
	ds_read_b128 v[92:95], v120 offset:6288
	s_waitcnt lgkmcnt(11)
	ds_read_b32 v114, v121 offset:16640
	v_add_f32_dpp v116, v116, v116 quad_perm:[2,3,0,1] row_mask:0xf bank_mask:0xf bound_ctrl:1
	s_mov_b64 exec, s[38:39]
	ds_write_b32 v121, v116 offset:23808
	s_mov_b64 exec, s[0:1]
	s_waitcnt lgkmcnt(9)
	v_pk_mul_f32 v[116:117], v[0:1], v[36:37]
	v_pk_fma_f32 v[36:37], v[72:73], v[36:37], v[104:105]
	v_pk_mul_f32 v[118:119], v[2:3], v[34:35]
	v_pk_fma_f32 v[34:35], v[74:75], v[34:35], v[106:107]
	v_pk_fma_f32 v[116:117], v[4:5], v[32:33], v[116:117]
	v_pk_fma_f32 v[32:33], v[76:77], v[32:33], v[108:109]
	v_pk_fma_f32 v[118:119], v[6:7], v[30:31], v[118:119]
	v_pk_fma_f32 v[30:31], v[78:79], v[30:31], v[110:111]
	ds_read_b128 v[0:3], v120 offset:2048
	ds_read_b128 v[4:7], v120 offset:2064
	ds_read_b128 v[72:75], v120 offset:10368
	ds_read_b128 v[76:79], v120 offset:10384
	v_pk_add_f32 v[116:117], v[116:117], v[118:119]
	v_pk_mul_f32 v[96:97], v[112:113], v[80:81] op_sel_hi:[0,1]
	v_pk_mul_f32 v[98:99], v[112:113], v[82:83] op_sel_hi:[0,1]
	v_add_f32_e32 v116, v116, v117
	v_pk_mul_f32 v[100:101], v[112:113], v[84:85] op_sel_hi:[0,1]
	v_pk_mul_f32 v[102:103], v[112:113], v[86:87] op_sel_hi:[0,1]
	v_add_f32_dpp v116, v116, v116 quad_perm:[1,0,3,2] row_mask:0xf bank_mask:0xf bound_ctrl:1
	ds_read_b128 v[80:83], v120 offset:6400
	ds_read_b128 v[84:87], v120 offset:6416
	s_waitcnt lgkmcnt(11)
	ds_read_b32 v112, v121 offset:16896
	v_add_f32_dpp v116, v116, v116 quad_perm:[2,3,0,1] row_mask:0xf bank_mask:0xf bound_ctrl:1
	s_mov_b64 exec, s[38:39]
	ds_write_b32 v121, v116 offset:24064
	s_mov_b64 exec, s[0:1]
	s_waitcnt lgkmcnt(9)
; #define LAS __attribute__((address_space(3)))
; __device__ __forceinline__ float quad_sum(float v) { v += dppf<0xB1>(v); v += dppf<0x4E>(v); return v; }
; __device__ __forceinline__ void gla_unit(const Params& P, LAS unsigned char* lds, int li, bool sample, int b, int h, const int tid) {
;     ...
;             for (int tok = 0; tok < ntok; ++tok) {
;                 const int tn = min(tok + 1, ntok - 1);
;                 f32x4 kn[2], qn[2], gn[2];
; #pragma unroll
;                 for (int i = 0; i < 2; ++i) { kn[i] = *(const LAS f32x4*)(ks + tn * 32 + 8 * dq + 4 * i); qn[i] = *(const LAS f32x4*)(qs + tn * 32 + 8 * dq + 4 * i); gn[i] = *(const LAS f32x4*)(gs + tn * 32 + 8 * dq + 4 * i); }
;                 const float vn = vs[tn * 64 + e];
;                 const f32x2 v2 = (f32x2){ve, ve};
;                 f32x2 oa[2];
; #pragma unroll
;                 for (int i = 0; i < 2; ++i) {
;                     S[2 * i] = S[2 * i] * (f32x2){gg[i][0], gg[i][1]} + (f32x2){kk[i][0], kk[i][1]} * v2; S[2 * i + 1] = S[2 * i + 1] * (f32x2){gg[i][2], gg[i][3]} + (f32x2){kk[i][2], kk[i][3]} * v2;
;                     oa[i] = (f32x2){qq[i][0], qq[i][1]} * S[2 * i] + (f32x2){qq[i][2], qq[i][3]} * S[2 * i + 1];
;                 }
;                 const f32x2 os2 = oa[0] + oa[1];
;                 const float o = quad_sum(os2[0] + os2[1]);
;                 if (dq == 0) os[tok * 64 + e] = o;
; #pragma unroll
;                 for (int i = 0; i < 2; ++i) { kk[i] = kn[i]; qq[i] = qn[i]; gg[i] = gn[i]; }
;                 ve = vn;
	v_pk_mul_f32 v[116:117], v[8:9], v[36:37]
	v_pk_fma_f32 v[36:37], v[16:17], v[36:37], v[96:97]
	v_pk_mul_f32 v[118:119], v[10:11], v[34:35]
	v_pk_fma_f32 v[34:35], v[18:19], v[34:35], v[98:99]
	v_pk_fma_f32 v[116:117], v[12:13], v[32:33], v[116:117]
	v_pk_fma_f32 v[32:33], v[20:21], v[32:33], v[100:101]
	v_pk_fma_f32 v[118:119], v[14:15], v[30:31], v[118:119]
	v_pk_fma_f32 v[30:31], v[22:23], v[30:31], v[102:103]
	ds_read_b128 v[8:11], v120 offset:2176
	ds_read_b128 v[12:15], v120 offset:2192
	ds_read_b128 v[16:19], v120 offset:10496
	ds_read_b128 v[20:23], v120 offset:10512
	v_pk_add_f32 v[116:117], v[116:117], v[118:119]
	v_pk_mul_f32 v[104:105], v[114:115], v[88:89] op_sel_hi:[0,1]
	v_pk_mul_f32 v[106:107], v[114:115], v[90:91] op_sel_hi:[0,1]
	v_add_f32_e32 v116, v116, v117
	v_pk_mul_f32 v[108:109], v[114:115], v[92:93] op_sel_hi:[0,1]
	v_pk_mul_f32 v[110:111], v[114:115], v[94:95] op_sel_hi:[0,1]
	v_add_f32_dpp v116, v116, v116 quad_perm:[1,0,3,2] row_mask:0xf bank_mask:0xf bound_ctrl:1
	ds_read_b128 v[88:91], v120 offset:6528
	ds_read_b128 v[92:95], v120 offset:6544
	s_waitcnt lgkmcnt(11)
	ds_read_b32 v114, v121 offset:17152
	v_add_f32_dpp v116, v116, v116 quad_perm:[2,3,0,1] row_mask:0xf bank_mask:0xf bound_ctrl:1
	s_mov_b64 exec, s[38:39]
	ds_write_b32 v121, v116 offset:24320
	s_mov_b64 exec, s[0:1]
	s_waitcnt lgkmcnt(9)
	v_pk_mul_f32 v[116:117], v[0:1], v[36:37]
	v_pk_fma_f32 v[36:37], v[72:73], v[36:37], v[104:105]
	v_pk_mul_f32 v[118:119], v[2:3], v[34:35]
	v_pk_fma_f32 v[34:35], v[74:75], v[34:35], v[106:107]
	v_pk_fma_f32 v[116:117], v[4:5], v[32:33], v[116:117]
	v_pk_fma_f32 v[32:33], v[76:77], v[32:33], v[108:109]
	v_pk_fma_f32 v[118:119], v[6:7], v[30:31], v[118:119]
	v_pk_fma_f32 v[30:31], v[78:79], v[30:31], v[110:111]
	ds_read_b128 v[0:3], v120 offset:2304
	ds_read_b128 v[4:7], v120 offset:2320
	ds_read_b128 v[72:75], v120 offset:10624
	ds_read_b128 v[76:79], v120 offset:10640
	v_pk_add_f32 v[116:117], v[116:117], v[118:119]
	v_pk_mul_f32 v[96:97], v[112:113], v[80:81] op_sel_hi:[0,1]
	v_pk_mul_f32 v[98:99], v[112:113], v[82:83] op_sel_hi:[0,1]
	v_add_f32_e32 v116, v116, v117
	v_pk_mul_f32 v[100:101], v[112:113], v[84:85] op_sel_hi:[0,1]
	v_pk_mul_f32 v[102:103], v[112:113], v[86:87] op_sel_hi:[0,1]
	v_add_f32_dpp v116, v116, v116 quad_perm:[1,0,3,2] row_mask:0xf bank_mask:0xf bound_ctrl:1
	ds_read_b128 v[80:83], v120 offset:6656
	ds_read_b128 v[84:87], v120 offset:6672
	s_waitcnt lgkmcnt(11)
	ds_read_b32 v112, v121 offset:17408
	v_add_f32_dpp v116, v116, v116 quad_perm:[2,3,0,1] row_mask:0xf bank_mask:0xf bound_ctrl:1
	s_mov_b64 exec, s[38:39]
	ds_write_b32 v121, v116 offset:24576
	s_mov_b64 exec, s[0:1]
	s_waitcnt lgkmcnt(9)
	v_pk_mul_f32 v[116:117], v[8:9], v[36:37]
	v_pk_fma_f32 v[36:37], v[16:17], v[36:37], v[96:97]
	v_pk_mul_f32 v[118:119], v[10:11], v[34:35]
	v_pk_fma_f32 v[34:35], v[18:19], v[34:35], v[98:99]
	v_pk_fma_f32 v[116:117], v[12:13], v[32:33], v[116:117]
	v_pk_fma_f32 v[32:33], v[20:21], v[32:33], v[100:101]
	v_pk_fma_f32 v[118:119], v[14:15], v[30:31], v[118:119]
	v_pk_fma_f32 v[30:31], v[22:23], v[30:31], v[102:103]
	ds_read_b128 v[8:11], v120 offset:2432
	ds_read_b128 v[12:15], v120 offset:2448
	ds_read_b128 v[16:19], v120 offset:10752
	ds_read_b128 v[20:23], v120 offset:10768
	v_pk_add_f32 v[116:117], v[116:117], v[118:119]
	v_pk_mul_f32 v[104:105], v[114:115], v[88:89] op_sel_hi:[0,1]
	v_pk_mul_f32 v[106:107], v[114:115], v[90:91] op_sel_hi:[0,1]
	v_add_f32_e32 v116, v116, v117
	v_pk_mul_f32 v[108:109], v[114:115], v[92:93] op_sel_hi:[0,1]
	v_pk_mul_f32 v[110:111], v[114:115], v[94:95] op_sel_hi:[0,1]
	v_add_f32_dpp v116, v116, v116 quad_perm:[1,0,3,2] row_mask:0xf bank_mask:0xf bound_ctrl:1
	ds_read_b128 v[88:91], v120 offset:6784
	ds_read_b128 v[92:95], v120 offset:6800
	s_waitcnt lgkmcnt(11)
	ds_read_b32 v114, v121 offset:17664
	v_add_f32_dpp v116, v116, v116 quad_perm:[2,3,0,1] row_mask:0xf bank_mask:0xf bound_ctrl:1
	s_mov_b64 exec, s[38:39]
	ds_write_b32 v121, v116 offset:24832
	s_mov_b64 exec, s[0:1]
	s_waitcnt lgkmcnt(9)
	v_pk_mul_f32 v[116:117], v[0:1], v[36:37]
	v_pk_fma_f32 v[36:37], v[72:73], v[36:37], v[104:105]
	v_pk_mul_f32 v[118:119], v[2:3], v[34:35]
	v_pk_fma_f32 v[34:35], v[74:75], v[34:35], v[106:107]
	v_pk_fma_f32 v[116:117], v[4:5], v[32:33], v[116:117]
	v_pk_fma_f32 v[32:33], v[76:77], v[32:33], v[108:109]
	v_pk_fma_f32 v[118:119], v[6:7], v[30:31], v[118:119]
	v_pk_fma_f32 v[30:31], v[78:79], v[30:31], v[110:111]
	ds_read_b128 v[0:3], v120 offset:2560
	ds_read_b128 v[4:7], v120 offset:2576
	ds_read_b128 v[72:75], v120 offset:10880
	ds_read_b128 v[76:79], v120 offset:10896
	v_pk_add_f32 v[116:117], v[116:117], v[118:119]
	v_pk_mul_f32 v[96:97], v[112:113], v[80:81] op_sel_hi:[0,1]
	v_pk_mul_f32 v[98:99], v[112:113], v[82:83] op_sel_hi:[0,1]
	v_add_f32_e32 v116, v116, v117
	v_pk_mul_f32 v[100:101], v[112:113], v[84:85] op_sel_hi:[0,1]
	v_pk_mul_f32 v[102:103], v[112:113], v[86:87] op_sel_hi:[0,1]
	v_add_f32_dpp v116, v116, v116 quad_perm:[1,0,3,2] row_mask:0xf bank_mask:0xf bound_ctrl:1
	ds_read_b128 v[80:83], v120 offset:6912
	ds_read_b128 v[84:87], v120 offset:6928
	s_waitcnt lgkmcnt(11)
	ds_read_b32 v112, v121 offset:17920
	v_add_f32_dpp v116, v116, v116 quad_perm:[2,3,0,1] row_mask:0xf bank_mask:0xf bound_ctrl:1
	s_mov_b64 exec, s[38:39]
	ds_write_b32 v121, v116 offset:25088
	s_mov_b64 exec, s[0:1]
	s_waitcnt lgkmcnt(9)
; #define LAS __attribute__((address_space(3)))
; __device__ __forceinline__ float quad_sum(float v) { v += dppf<0xB1>(v); v += dppf<0x4E>(v); return v; }
; __device__ __forceinline__ void gla_unit(const Params& P, LAS unsigned char* lds, int li, bool sample, int b, int h, const int tid) {
;     ...
;             for (int tok = 0; tok < ntok; ++tok) {
;                 const int tn = min(tok + 1, ntok - 1);
;                 f32x4 kn[2], qn[2], gn[2];
; #pragma unroll
;                 for (int i = 0; i < 2; ++i) { kn[i] = *(const LAS f32x4*)(ks + tn * 32 + 8 * dq + 4 * i); qn[i] = *(const LAS f32x4*)(qs + tn * 32 + 8 * dq + 4 * i); gn[i] = *(const LAS f32x4*)(gs + tn * 32 + 8 * dq + 4 * i); }
;                 const float vn = vs[tn * 64 + e];
;                 const f32x2 v2 = (f32x2){ve, ve};
;                 f32x2 oa[2];
; #pragma unroll
;                 for (int i = 0; i < 2; ++i) {
;                     S[2 * i] = S[2 * i] * (f32x2){gg[i][0], gg[i][1]} + (f32x2){kk[i][0], kk[i][1]} * v2; S[2 * i + 1] = S[2 * i + 1] * (f32x2){gg[i][2], gg[i][3]} + (f32x2){kk[i][2], kk[i][3]} * v2;
;                     oa[i] = (f32x2){qq[i][0], qq[i][1]} * S[2 * i] + (f32x2){qq[i][2], qq[i][3]} * S[2 * i + 1];
;                 }
;                 const f32x2 os2 = oa[0] + oa[1];
;                 const float o = quad_sum(os2[0] + os2[1]);
;                 if (dq == 0) os[tok * 64 + e] = o;
; #pragma unroll
;                 for (int i = 0; i < 2; ++i) { kk[i] = kn[i]; qq[i] = qn[i]; gg[i] = gn[i]; }
;                 ve = vn;
	v_pk_mul_f32 v[116:117], v[8:9], v[36:37]
	v_pk_fma_f32 v[36:37], v[16:17], v[36:37], v[96:97]
	v_pk_mul_f32 v[118:119], v[10:11], v[34:35]
	v_pk_fma_f32 v[34:35], v[18:19], v[34:35], v[98:99]
	v_pk_fma_f32 v[116:117], v[12:13], v[32:33], v[116:117]
	v_pk_fma_f32 v[32:33], v[20:21], v[32:33], v[100:101]
	v_pk_fma_f32 v[118:119], v[14:15], v[30:31], v[118:119]
	v_pk_fma_f32 v[30:31], v[22:23], v[30:31], v[102:103]
	ds_read_b128 v[8:11], v120 offset:2688
	ds_read_b128 v[12:15], v120 offset:2704
	ds_read_b128 v[16:19], v120 offset:11008
	ds_read_b128 v[20:23], v120 offset:11024
	v_pk_add_f32 v[116:117], v[116:117], v[118:119]
	v_pk_mul_f32 v[104:105], v[114:115], v[88:89] op_sel_hi:[0,1]
	v_pk_mul_f32 v[106:107], v[114:115], v[90:91] op_sel_hi:[0,1]
	v_add_f32_e32 v116, v116, v117
	v_pk_mul_f32 v[108:109], v[114:115], v[92:93] op_sel_hi:[0,1]
	v_pk_mul_f32 v[110:111], v[114:115], v[94:95] op_sel_hi:[0,1]
	v_add_f32_dpp v116, v116, v116 quad_perm:[1,0,3,2] row_mask:0xf bank_mask:0xf bound_ctrl:1
	ds_read_b128 v[88:91], v120 offset:7040
	ds_read_b128 v[92:95], v120 offset:7056
	s_waitcnt lgkmcnt(11)
	ds_read_b32 v114, v121 offset:18176
	v_add_f32_dpp v116, v116, v116 quad_perm:[2,3,0,1] row_mask:0xf bank_mask:0xf bound_ctrl:1
	s_mov_b64 exec, s[38:39]
	ds_write_b32 v121, v116 offset:25344
	s_mov_b64 exec, s[0:1]
	s_waitcnt lgkmcnt(9)
	v_pk_mul_f32 v[116:117], v[0:1], v[36:37]
	v_pk_fma_f32 v[36:37], v[72:73], v[36:37], v[104:105]
	v_pk_mul_f32 v[118:119], v[2:3], v[34:35]
	v_pk_fma_f32 v[34:35], v[74:75], v[34:35], v[106:107]
	v_pk_fma_f32 v[116:117], v[4:5], v[32:33], v[116:117]
	v_pk_fma_f32 v[32:33], v[76:77], v[32:33], v[108:109]
	v_pk_fma_f32 v[118:119], v[6:7], v[30:31], v[118:119]
	v_pk_fma_f32 v[30:31], v[78:79], v[30:31], v[110:111]
	ds_read_b128 v[0:3], v120 offset:2816
	ds_read_b128 v[4:7], v120 offset:2832
	ds_read_b128 v[72:75], v120 offset:11136
	ds_read_b128 v[76:79], v120 offset:11152
	v_pk_add_f32 v[116:117], v[116:117], v[118:119]
	v_pk_mul_f32 v[96:97], v[112:113], v[80:81] op_sel_hi:[0,1]
	v_pk_mul_f32 v[98:99], v[112:113], v[82:83] op_sel_hi:[0,1]
	v_add_f32_e32 v116, v116, v117
	v_pk_mul_f32 v[100:101], v[112:113], v[84:85] op_sel_hi:[0,1]
	v_pk_mul_f32 v[102:103], v[112:113], v[86:87] op_sel_hi:[0,1]
	v_add_f32_dpp v116, v116, v116 quad_perm:[1,0,3,2] row_mask:0xf bank_mask:0xf bound_ctrl:1
	ds_read_b128 v[80:83], v120 offset:7168
	ds_read_b128 v[84:87], v120 offset:7184
	s_waitcnt lgkmcnt(11)
	ds_read_b32 v112, v121 offset:18432
	v_add_f32_dpp v116, v116, v116 quad_perm:[2,3,0,1] row_mask:0xf bank_mask:0xf bound_ctrl:1
	s_mov_b64 exec, s[38:39]
	ds_write_b32 v121, v116 offset:25600
	s_mov_b64 exec, s[0:1]
	s_waitcnt lgkmcnt(9)
	v_pk_mul_f32 v[116:117], v[8:9], v[36:37]
	v_pk_fma_f32 v[36:37], v[16:17], v[36:37], v[96:97]
	v_pk_mul_f32 v[118:119], v[10:11], v[34:35]
	v_pk_fma_f32 v[34:35], v[18:19], v[34:35], v[98:99]
	v_pk_fma_f32 v[116:117], v[12:13], v[32:33], v[116:117]
	v_pk_fma_f32 v[32:33], v[20:21], v[32:33], v[100:101]
	v_pk_fma_f32 v[118:119], v[14:15], v[30:31], v[118:119]
	v_pk_fma_f32 v[30:31], v[22:23], v[30:31], v[102:103]
	ds_read_b128 v[8:11], v120 offset:2944
	ds_read_b128 v[12:15], v120 offset:2960
	ds_read_b128 v[16:19], v120 offset:11264
	ds_read_b128 v[20:23], v120 offset:11280
	v_pk_add_f32 v[116:117], v[116:117], v[118:119]
	v_pk_mul_f32 v[104:105], v[114:115], v[88:89] op_sel_hi:[0,1]
	v_pk_mul_f32 v[106:107], v[114:115], v[90:91] op_sel_hi:[0,1]
	v_add_f32_e32 v116, v116, v117
	v_pk_mul_f32 v[108:109], v[114:115], v[92:93] op_sel_hi:[0,1]
	v_pk_mul_f32 v[110:111], v[114:115], v[94:95] op_sel_hi:[0,1]
	v_add_f32_dpp v116, v116, v116 quad_perm:[1,0,3,2] row_mask:0xf bank_mask:0xf bound_ctrl:1
	ds_read_b128 v[88:91], v120 offset:7296
	ds_read_b128 v[92:95], v120 offset:7312
	s_waitcnt lgkmcnt(11)
	ds_read_b32 v114, v121 offset:18688
	v_add_f32_dpp v116, v116, v116 quad_perm:[2,3,0,1] row_mask:0xf bank_mask:0xf bound_ctrl:1
	s_mov_b64 exec, s[38:39]
	ds_write_b32 v121, v116 offset:25856
	s_mov_b64 exec, s[0:1]
	s_waitcnt lgkmcnt(9)
	v_pk_mul_f32 v[116:117], v[0:1], v[36:37]
	v_pk_fma_f32 v[36:37], v[72:73], v[36:37], v[104:105]
	v_pk_mul_f32 v[118:119], v[2:3], v[34:35]
	v_pk_fma_f32 v[34:35], v[74:75], v[34:35], v[106:107]
	v_pk_fma_f32 v[116:117], v[4:5], v[32:33], v[116:117]
	v_pk_fma_f32 v[32:33], v[76:77], v[32:33], v[108:109]
	v_pk_fma_f32 v[118:119], v[6:7], v[30:31], v[118:119]
	v_pk_fma_f32 v[30:31], v[78:79], v[30:31], v[110:111]
	ds_read_b128 v[0:3], v120 offset:3072
	ds_read_b128 v[4:7], v120 offset:3088
	ds_read_b128 v[72:75], v120 offset:11392
	ds_read_b128 v[76:79], v120 offset:11408
	v_pk_add_f32 v[116:117], v[116:117], v[118:119]
	v_pk_mul_f32 v[96:97], v[112:113], v[80:81] op_sel_hi:[0,1]
	v_pk_mul_f32 v[98:99], v[112:113], v[82:83] op_sel_hi:[0,1]
	v_add_f32_e32 v116, v116, v117
	v_pk_mul_f32 v[100:101], v[112:113], v[84:85] op_sel_hi:[0,1]
	v_pk_mul_f32 v[102:103], v[112:113], v[86:87] op_sel_hi:[0,1]
	v_add_f32_dpp v116, v116, v116 quad_perm:[1,0,3,2] row_mask:0xf bank_mask:0xf bound_ctrl:1
	ds_read_b128 v[80:83], v120 offset:7424
	ds_read_b128 v[84:87], v120 offset:7440
	s_waitcnt lgkmcnt(11)
	ds_read_b32 v112, v121 offset:18944
	v_add_f32_dpp v116, v116, v116 quad_perm:[2,3,0,1] row_mask:0xf bank_mask:0xf bound_ctrl:1
	s_mov_b64 exec, s[38:39]
	ds_write_b32 v121, v116 offset:26112
	s_mov_b64 exec, s[0:1]
	s_waitcnt lgkmcnt(9)
; #define LAS __attribute__((address_space(3)))
; __device__ __forceinline__ float quad_sum(float v) { v += dppf<0xB1>(v); v += dppf<0x4E>(v); return v; }
; __device__ __forceinline__ void gla_unit(const Params& P, LAS unsigned char* lds, int li, bool sample, int b, int h, const int tid) {
;     ...
;             for (int tok = 0; tok < ntok; ++tok) {
;                 const int tn = min(tok + 1, ntok - 1);
;                 f32x4 kn[2], qn[2], gn[2];
; #pragma unroll
;                 for (int i = 0; i < 2; ++i) { kn[i] = *(const LAS f32x4*)(ks + tn * 32 + 8 * dq + 4 * i); qn[i] = *(const LAS f32x4*)(qs + tn * 32 + 8 * dq + 4 * i); gn[i] = *(const LAS f32x4*)(gs + tn * 32 + 8 * dq + 4 * i); }
;                 const float vn = vs[tn * 64 + e];
;                 const f32x2 v2 = (f32x2){ve, ve};
;                 f32x2 oa[2];
; #pragma unroll
;                 for (int i = 0; i < 2; ++i) {
;                     S[2 * i] = S[2 * i] * (f32x2){gg[i][0], gg[i][1]} + (f32x2){kk[i][0], kk[i][1]} * v2; S[2 * i + 1] = S[2 * i + 1] * (f32x2){gg[i][2], gg[i][3]} + (f32x2){kk[i][2], kk[i][3]} * v2;
;                     oa[i] = (f32x2){qq[i][0], qq[i][1]} * S[2 * i] + (f32x2){qq[i][2], qq[i][3]} * S[2 * i + 1];
;                 }
;                 const f32x2 os2 = oa[0] + oa[1];
;                 const float o = quad_sum(os2[0] + os2[1]);
;                 if (dq == 0) os[tok * 64 + e] = o;
; #pragma unroll
;                 for (int i = 0; i < 2; ++i) { kk[i] = kn[i]; qq[i] = qn[i]; gg[i] = gn[i]; }
;                 ve = vn;
	v_pk_mul_f32 v[116:117], v[8:9], v[36:37]
	v_pk_fma_f32 v[36:37], v[16:17], v[36:37], v[96:97]
	v_pk_mul_f32 v[118:119], v[10:11], v[34:35]
	v_pk_fma_f32 v[34:35], v[18:19], v[34:35], v[98:99]
	v_pk_fma_f32 v[116:117], v[12:13], v[32:33], v[116:117]
	v_pk_fma_f32 v[32:33], v[20:21], v[32:33], v[100:101]
	v_pk_fma_f32 v[118:119], v[14:15], v[30:31], v[118:119]
	v_pk_fma_f32 v[30:31], v[22:23], v[30:31], v[102:103]
	ds_read_b128 v[8:11], v120 offset:3200
	ds_read_b128 v[12:15], v120 offset:3216
	ds_read_b128 v[16:19], v120 offset:11520
	ds_read_b128 v[20:23], v120 offset:11536
	v_pk_add_f32 v[116:117], v[116:117], v[118:119]
	v_pk_mul_f32 v[104:105], v[114:115], v[88:89] op_sel_hi:[0,1]
	v_pk_mul_f32 v[106:107], v[114:115], v[90:91] op_sel_hi:[0,1]
	v_add_f32_e32 v116, v116, v117
	v_pk_mul_f32 v[108:109], v[114:115], v[92:93] op_sel_hi:[0,1]
	v_pk_mul_f32 v[110:111], v[114:115], v[94:95] op_sel_hi:[0,1]
	v_add_f32_dpp v116, v116, v116 quad_perm:[1,0,3,2] row_mask:0xf bank_mask:0xf bound_ctrl:1
	ds_read_b128 v[88:91], v120 offset:7552
	ds_read_b128 v[92:95], v120 offset:7568
	s_waitcnt lgkmcnt(11)
	ds_read_b32 v114, v121 offset:19200
	v_add_f32_dpp v116, v116, v116 quad_perm:[2,3,0,1] row_mask:0xf bank_mask:0xf bound_ctrl:1
	s_mov_b64 exec, s[38:39]
	ds_write_b32 v121, v116 offset:26368
	s_mov_b64 exec, s[0:1]
	s_waitcnt lgkmcnt(9)
	v_pk_mul_f32 v[116:117], v[0:1], v[36:37]
	v_pk_fma_f32 v[36:37], v[72:73], v[36:37], v[104:105]
	v_pk_mul_f32 v[118:119], v[2:3], v[34:35]
	v_pk_fma_f32 v[34:35], v[74:75], v[34:35], v[106:107]
	v_pk_fma_f32 v[116:117], v[4:5], v[32:33], v[116:117]
	v_pk_fma_f32 v[32:33], v[76:77], v[32:33], v[108:109]
	v_pk_fma_f32 v[118:119], v[6:7], v[30:31], v[118:119]
	v_pk_fma_f32 v[30:31], v[78:79], v[30:31], v[110:111]
	ds_read_b128 v[0:3], v120 offset:3328
	ds_read_b128 v[4:7], v120 offset:3344
	ds_read_b128 v[72:75], v120 offset:11648
	ds_read_b128 v[76:79], v120 offset:11664
	v_pk_add_f32 v[116:117], v[116:117], v[118:119]
	v_pk_mul_f32 v[96:97], v[112:113], v[80:81] op_sel_hi:[0,1]
	v_pk_mul_f32 v[98:99], v[112:113], v[82:83] op_sel_hi:[0,1]
	v_add_f32_e32 v116, v116, v117
	v_pk_mul_f32 v[100:101], v[112:113], v[84:85] op_sel_hi:[0,1]
	v_pk_mul_f32 v[102:103], v[112:113], v[86:87] op_sel_hi:[0,1]
	v_add_f32_dpp v116, v116, v116 quad_perm:[1,0,3,2] row_mask:0xf bank_mask:0xf bound_ctrl:1
	ds_read_b128 v[80:83], v120 offset:7680
	ds_read_b128 v[84:87], v120 offset:7696
	s_waitcnt lgkmcnt(11)
	ds_read_b32 v112, v121 offset:19456
	v_add_f32_dpp v116, v116, v116 quad_perm:[2,3,0,1] row_mask:0xf bank_mask:0xf bound_ctrl:1
	s_mov_b64 exec, s[38:39]
	ds_write_b32 v121, v116 offset:26624
	s_mov_b64 exec, s[0:1]
	s_waitcnt lgkmcnt(9)
	v_pk_mul_f32 v[116:117], v[8:9], v[36:37]
	v_pk_fma_f32 v[36:37], v[16:17], v[36:37], v[96:97]
	v_pk_mul_f32 v[118:119], v[10:11], v[34:35]
	v_pk_fma_f32 v[34:35], v[18:19], v[34:35], v[98:99]
	v_pk_fma_f32 v[116:117], v[12:13], v[32:33], v[116:117]
	v_pk_fma_f32 v[32:33], v[20:21], v[32:33], v[100:101]
	v_pk_fma_f32 v[118:119], v[14:15], v[30:31], v[118:119]
	v_pk_fma_f32 v[30:31], v[22:23], v[30:31], v[102:103]
	ds_read_b128 v[8:11], v120 offset:3456
	ds_read_b128 v[12:15], v120 offset:3472
	ds_read_b128 v[16:19], v120 offset:11776
	ds_read_b128 v[20:23], v120 offset:11792
	v_pk_add_f32 v[116:117], v[116:117], v[118:119]
	v_pk_mul_f32 v[104:105], v[114:115], v[88:89] op_sel_hi:[0,1]
	v_pk_mul_f32 v[106:107], v[114:115], v[90:91] op_sel_hi:[0,1]
	v_add_f32_e32 v116, v116, v117
	v_pk_mul_f32 v[108:109], v[114:115], v[92:93] op_sel_hi:[0,1]
	v_pk_mul_f32 v[110:111], v[114:115], v[94:95] op_sel_hi:[0,1]
	v_add_f32_dpp v116, v116, v116 quad_perm:[1,0,3,2] row_mask:0xf bank_mask:0xf bound_ctrl:1
	ds_read_b128 v[88:91], v120 offset:7808
	ds_read_b128 v[92:95], v120 offset:7824
	s_waitcnt lgkmcnt(11)
	ds_read_b32 v114, v121 offset:19712
	v_add_f32_dpp v116, v116, v116 quad_perm:[2,3,0,1] row_mask:0xf bank_mask:0xf bound_ctrl:1
	s_mov_b64 exec, s[38:39]
	ds_write_b32 v121, v116 offset:26880
	s_mov_b64 exec, s[0:1]
	s_waitcnt lgkmcnt(9)
	v_pk_mul_f32 v[116:117], v[0:1], v[36:37]
	v_pk_fma_f32 v[36:37], v[72:73], v[36:37], v[104:105]
	v_pk_mul_f32 v[118:119], v[2:3], v[34:35]
	v_pk_fma_f32 v[34:35], v[74:75], v[34:35], v[106:107]
	v_pk_fma_f32 v[116:117], v[4:5], v[32:33], v[116:117]
	v_pk_fma_f32 v[32:33], v[76:77], v[32:33], v[108:109]
	v_pk_fma_f32 v[118:119], v[6:7], v[30:31], v[118:119]
	v_pk_fma_f32 v[30:31], v[78:79], v[30:31], v[110:111]
	ds_read_b128 v[0:3], v120 offset:3584
	ds_read_b128 v[4:7], v120 offset:3600
	ds_read_b128 v[72:75], v120 offset:11904
	ds_read_b128 v[76:79], v120 offset:11920
	v_pk_add_f32 v[116:117], v[116:117], v[118:119]
	v_pk_mul_f32 v[96:97], v[112:113], v[80:81] op_sel_hi:[0,1]
	v_pk_mul_f32 v[98:99], v[112:113], v[82:83] op_sel_hi:[0,1]
	v_add_f32_e32 v116, v116, v117
	v_pk_mul_f32 v[100:101], v[112:113], v[84:85] op_sel_hi:[0,1]
	v_pk_mul_f32 v[102:103], v[112:113], v[86:87] op_sel_hi:[0,1]
	v_add_f32_dpp v116, v116, v116 quad_perm:[1,0,3,2] row_mask:0xf bank_mask:0xf bound_ctrl:1
	ds_read_b128 v[80:83], v120 offset:7936
	ds_read_b128 v[84:87], v120 offset:7952
	s_waitcnt lgkmcnt(11)
; #define LAS __attribute__((address_space(3)))
; __device__ __forceinline__ float quad_sum(float v) { v += dppf<0xB1>(v); v += dppf<0x4E>(v); return v; }
; __device__ __forceinline__ void gla_unit(const Params& P, LAS unsigned char* lds, int li, bool sample, int b, int h, const int tid) {
;     ...
;             for (int tok = 0; tok < ntok; ++tok) {
;                 const int tn = min(tok + 1, ntok - 1);
;                 f32x4 kn[2], qn[2], gn[2];
; #pragma unroll
;                 for (int i = 0; i < 2; ++i) { kn[i] = *(const LAS f32x4*)(ks + tn * 32 + 8 * dq + 4 * i); qn[i] = *(const LAS f32x4*)(qs + tn * 32 + 8 * dq + 4 * i); gn[i] = *(const LAS f32x4*)(gs + tn * 32 + 8 * dq + 4 * i); }
;                 const float vn = vs[tn * 64 + e];
;                 const f32x2 v2 = (f32x2){ve, ve};
;                 f32x2 oa[2];
; #pragma unroll
;                 for (int i = 0; i < 2; ++i) {
;                     S[2 * i] = S[2 * i] * (f32x2){gg[i][0], gg[i][1]} + (f32x2){kk[i][0], kk[i][1]} * v2; S[2 * i + 1] = S[2 * i + 1] * (f32x2){gg[i][2], gg[i][3]} + (f32x2){kk[i][2], kk[i][3]} * v2;
;                     oa[i] = (f32x2){qq[i][0], qq[i][1]} * S[2 * i] + (f32x2){qq[i][2], qq[i][3]} * S[2 * i + 1];
;                 }
;                 const f32x2 os2 = oa[0] + oa[1];
;                 const float o = quad_sum(os2[0] + os2[1]);
;                 if (dq == 0) os[tok * 64 + e] = o;
; #pragma unroll
;                 for (int i = 0; i < 2; ++i) { kk[i] = kn[i]; qq[i] = qn[i]; gg[i] = gn[i]; }
;                 ve = vn;
	ds_read_b32 v112, v121 offset:19968
	v_add_f32_dpp v116, v116, v116 quad_perm:[2,3,0,1] row_mask:0xf bank_mask:0xf bound_ctrl:1
	s_mov_b64 exec, s[38:39]
	ds_write_b32 v121, v116 offset:27136
	s_mov_b64 exec, s[0:1]
	s_waitcnt lgkmcnt(9)
	v_pk_mul_f32 v[116:117], v[8:9], v[36:37]
	v_pk_fma_f32 v[36:37], v[16:17], v[36:37], v[96:97]
	v_pk_mul_f32 v[118:119], v[10:11], v[34:35]
	v_pk_fma_f32 v[34:35], v[18:19], v[34:35], v[98:99]
	v_pk_fma_f32 v[116:117], v[12:13], v[32:33], v[116:117]
	v_pk_fma_f32 v[32:33], v[20:21], v[32:33], v[100:101]
	v_pk_fma_f32 v[118:119], v[14:15], v[30:31], v[118:119]
	v_pk_fma_f32 v[30:31], v[22:23], v[30:31], v[102:103]
	ds_read_b128 v[8:11], v120 offset:3712
	ds_read_b128 v[12:15], v120 offset:3728
	ds_read_b128 v[16:19], v120 offset:12032
	ds_read_b128 v[20:23], v120 offset:12048
	v_pk_add_f32 v[116:117], v[116:117], v[118:119]
	v_pk_mul_f32 v[104:105], v[114:115], v[88:89] op_sel_hi:[0,1]
	v_pk_mul_f32 v[106:107], v[114:115], v[90:91] op_sel_hi:[0,1]
	v_add_f32_e32 v116, v116, v117
	v_pk_mul_f32 v[108:109], v[114:115], v[92:93] op_sel_hi:[0,1]
	v_pk_mul_f32 v[110:111], v[114:115], v[94:95] op_sel_hi:[0,1]
	v_add_f32_dpp v116, v116, v116 quad_perm:[1,0,3,2] row_mask:0xf bank_mask:0xf bound_ctrl:1
	ds_read_b128 v[88:91], v120 offset:8064
	ds_read_b128 v[92:95], v120 offset:8080
	s_waitcnt lgkmcnt(11)
	ds_read_b32 v114, v121 offset:20224
	v_add_f32_dpp v116, v116, v116 quad_perm:[2,3,0,1] row_mask:0xf bank_mask:0xf bound_ctrl:1
	s_mov_b64 exec, s[38:39]
	ds_write_b32 v121, v116 offset:27392
	s_mov_b64 exec, s[0:1]
	s_waitcnt lgkmcnt(9)
	v_pk_mul_f32 v[116:117], v[0:1], v[36:37]
	v_pk_fma_f32 v[36:37], v[72:73], v[36:37], v[104:105]
	v_pk_mul_f32 v[118:119], v[2:3], v[34:35]
	v_pk_fma_f32 v[34:35], v[74:75], v[34:35], v[106:107]
	v_pk_fma_f32 v[116:117], v[4:5], v[32:33], v[116:117]
	v_pk_fma_f32 v[32:33], v[76:77], v[32:33], v[108:109]
	v_pk_fma_f32 v[118:119], v[6:7], v[30:31], v[118:119]
	v_pk_fma_f32 v[30:31], v[78:79], v[30:31], v[110:111]
	ds_read_b128 v[0:3], v120 offset:3840
	ds_read_b128 v[4:7], v120 offset:3856
	ds_read_b128 v[72:75], v120 offset:12160
	ds_read_b128 v[76:79], v120 offset:12176
	v_pk_add_f32 v[116:117], v[116:117], v[118:119]
	v_pk_mul_f32 v[96:97], v[112:113], v[80:81] op_sel_hi:[0,1]
	v_pk_mul_f32 v[98:99], v[112:113], v[82:83] op_sel_hi:[0,1]
	v_add_f32_e32 v116, v116, v117
	v_pk_mul_f32 v[100:101], v[112:113], v[84:85] op_sel_hi:[0,1]
	v_pk_mul_f32 v[102:103], v[112:113], v[86:87] op_sel_hi:[0,1]
	v_add_f32_dpp v116, v116, v116 quad_perm:[1,0,3,2] row_mask:0xf bank_mask:0xf bound_ctrl:1
	s_nop 1
	v_add_f32_dpp v116, v116, v116 quad_perm:[2,3,0,1] row_mask:0xf bank_mask:0xf bound_ctrl:1
	s_mov_b64 exec, s[38:39]
	ds_write_b32 v121, v116 offset:27648
	s_mov_b64 exec, s[0:1]
	s_waitcnt lgkmcnt(6)
	v_pk_mul_f32 v[116:117], v[8:9], v[36:37]
	v_pk_fma_f32 v[36:37], v[16:17], v[36:37], v[96:97]
	v_pk_mul_f32 v[118:119], v[10:11], v[34:35]
	v_pk_fma_f32 v[34:35], v[18:19], v[34:35], v[98:99]
	v_pk_fma_f32 v[116:117], v[12:13], v[32:33], v[116:117]
	v_pk_fma_f32 v[32:33], v[20:21], v[32:33], v[100:101]
	v_pk_fma_f32 v[118:119], v[14:15], v[30:31], v[118:119]
	v_pk_fma_f32 v[30:31], v[22:23], v[30:31], v[102:103]
	ds_read_b128 v[8:11], v120 offset:3968
	ds_read_b128 v[12:15], v120 offset:3984
	v_pk_add_f32 v[116:117], v[116:117], v[118:119]
	v_pk_mul_f32 v[104:105], v[114:115], v[88:89] op_sel_hi:[0,1]
	v_pk_mul_f32 v[106:107], v[114:115], v[90:91] op_sel_hi:[0,1]
	v_add_f32_e32 v116, v116, v117
	v_pk_mul_f32 v[108:109], v[114:115], v[92:93] op_sel_hi:[0,1]
	v_pk_mul_f32 v[110:111], v[114:115], v[94:95] op_sel_hi:[0,1]
	v_add_f32_dpp v116, v116, v116 quad_perm:[1,0,3,2] row_mask:0xf bank_mask:0xf bound_ctrl:1
	s_nop 1
	v_add_f32_dpp v116, v116, v116 quad_perm:[2,3,0,1] row_mask:0xf bank_mask:0xf bound_ctrl:1
	s_mov_b64 exec, s[38:39]
	ds_write_b32 v121, v116 offset:27904
	s_mov_b64 exec, s[0:1]
	s_waitcnt lgkmcnt(4)
	v_pk_mul_f32 v[116:117], v[0:1], v[36:37]
	v_pk_fma_f32 v[36:37], v[72:73], v[36:37], v[104:105]
	v_pk_mul_f32 v[118:119], v[2:3], v[34:35]
	v_pk_fma_f32 v[34:35], v[74:75], v[34:35], v[106:107]
	v_pk_fma_f32 v[116:117], v[4:5], v[32:33], v[116:117]
	v_pk_fma_f32 v[32:33], v[76:77], v[32:33], v[108:109]
	v_pk_fma_f32 v[118:119], v[6:7], v[30:31], v[118:119]
	v_pk_fma_f32 v[30:31], v[78:79], v[30:31], v[110:111]
	v_pk_add_f32 v[116:117], v[116:117], v[118:119]
	v_add_f32_e32 v116, v116, v117
	s_nop 1
	v_add_f32_dpp v116, v116, v116 quad_perm:[1,0,3,2] row_mask:0xf bank_mask:0xf bound_ctrl:1
	s_nop 1
	v_add_f32_dpp v116, v116, v116 quad_perm:[2,3,0,1] row_mask:0xf bank_mask:0xf bound_ctrl:1
	s_mov_b64 exec, s[38:39]
	ds_write_b32 v121, v116 offset:28160
	s_mov_b64 exec, s[0:1]
	s_waitcnt lgkmcnt(2)
	v_pk_mul_f32 v[116:117], v[8:9], v[36:37]
	v_pk_mul_f32 v[118:119], v[10:11], v[34:35]
	v_pk_fma_f32 v[116:117], v[12:13], v[32:33], v[116:117]
	v_pk_fma_f32 v[118:119], v[14:15], v[30:31], v[118:119]
	v_pk_add_f32 v[116:117], v[116:117], v[118:119]
	v_add_f32_e32 v116, v116, v117
	s_nop 1
	v_add_f32_dpp v116, v116, v116 quad_perm:[1,0,3,2] row_mask:0xf bank_mask:0xf bound_ctrl:1
	s_nop 1
	v_add_f32_dpp v116, v116, v116 quad_perm:[2,3,0,1] row_mask:0xf bank_mask:0xf bound_ctrl:1
	s_mov_b64 exec, s[38:39]
	ds_write_b32 v121, v116 offset:28416
	s_mov_b64 exec, s[0:1]
